# NSA selected-block loop: ALiBi key term carried in the QK accumulator C input (30 v_fmac per block removed)
# speedup vs baseline: 1.1195x; 1.0022x over previous
;     ...
;   const bf16x8 ones = bf16x8{0x3F80, 0x3F80, 0x3F80, 0x3F80, 0x3F80, 0x3F80, 0x3F80, 0x3F80};
;   f32x4 L[NQ * NMAP];
; #pragma unroll
;   for (int i = 0; i < NQ * NMAP; ++i) L[i] = f32x4{0.f, 0.f, 0.f, 0.f};
;   int nxt = next_tile(kt);
;   {
;     u32x4 fk[TK][2], fv[TK][2];
; #pragma unroll
;     for (int t = 0; t < TK; ++t)
; #pragma unroll
;       for (int i = 0; i < 2; ++i) {
;         fk[t][i] = *(const u32x4*)(gk + (size_t)((kt + t) * 64 + i * 32) * kstride);
;         fv[t][i] = *(const u32x4*)(gv + (size_t)(i * 32) * vtstride + (kt + t) * 64);
;       }
;     if (nxt < kt_end) gload(nxt);
;     hook();
;     __syncthreads();
; #pragma unroll
;     for (int t = 0; t < TK; ++t)
; #pragma unroll
;       for (int i = 0; i < 2; ++i) {
;         *(u32x4*)(wk + t * TSZ + i * 32 * 64) = fk[t][i];
;         *(u32x4*)(wv + t * TSZ + i * 32 * 72) = fv[t][i];
;       }
;   }
;   __syncthreads();
;   int stg = 0;
.LBB0_131:
	v_lshrrev_b32_e32 v36, 4, v37
	v_lshlrev_b32_e32 v39, 7, v2
	v_lshlrev_b32_e32 v2, 4, v2
	v_xor_b32_e32 v40, v36, v37
	v_add3_u32 v153, v39, v2, v0
	v_bfe_u32 v0, v37, 1, 3
	v_and_b32_e32 v3, 15, v37
	v_bfe_u32 v38, v37, 4, 2
	v_lshlrev_b32_e32 v40, 4, v40
	s_movk_i32 s0, 0x70
	v_bitop3_b32 v2, v36, v0, 3 bitop3:0x6c
	v_and_or_b32 v152, v40, s0, v39
	v_lshlrev_b32_e32 v155, 7, v3
	v_mul_u32_u24_e32 v156, 0x90, v3
	v_lshlrev_b32_e32 v157, 4, v2
	v_bitop3_b32 v0, v38, v0, 4 bitop3:0x36
	v_mov_b32_e32 v2, v1
	v_mov_b32_e32 v3, v1
	s_waitcnt lgkmcnt(0)
	s_barrier
	s_waitcnt vmcnt(3)
	ds_write_b128 v152, v[20:23]
	s_waitcnt vmcnt(2)
	ds_write_b128 v153, v[24:27] offset:9216
	s_waitcnt vmcnt(1)
	ds_write_b128 v152, v[28:31] offset:4096
	s_waitcnt vmcnt(0)
	ds_write_b128 v153, v[32:35] offset:13824
	s_mov_b64 s[0:1], 0x20000
	v_lshlrev_b32_e32 v154, 2, v38
	v_lshlrev_b32_e32 v158, 4, v0
	v_mov_b32_e32 v0, v1
	v_mov_b32_e32 v20, 0
	v_mov_b64_e32 v[58:59], v[2:3]
	v_mov_b64_e32 v[38:39], v[2:3]
	v_lshl_add_u64 v[148:149], v[146:147], 0, s[0:1]
	s_mov_b32 s47, 0
	v_mov_b64_e32 v[56:57], v[0:1]
	v_mov_b64_e32 v[36:37], v[0:1]
	v_mov_b32_e32 v21, v20
	v_mov_b32_e32 v22, v20
	v_mov_b32_e32 v23, v20
	v_mov_b32_e32 v24, v20
	v_mov_b32_e32 v25, v20
	v_mov_b32_e32 v26, v20
	v_mov_b32_e32 v27, v20
	v_mov_b32_e32 v28, v20
	v_mov_b32_e32 v29, v20
	v_mov_b32_e32 v30, v20
	v_mov_b32_e32 v31, v20
	v_mov_b32_e32 v32, v20
	v_mov_b32_e32 v33, v20
	v_mov_b32_e32 v34, v20
	v_mov_b32_e32 v35, v20
	v_mov_b32_e32 v40, v20
	v_mov_b32_e32 v41, v20
	v_mov_b32_e32 v42, v20
	v_mov_b32_e32 v43, v20
	v_mov_b32_e32 v44, v20
	v_mov_b32_e32 v45, v20
	v_mov_b32_e32 v46, v20
	v_mov_b32_e32 v47, v20
	v_mov_b32_e32 v48, v20
	v_mov_b32_e32 v49, v20
	v_mov_b32_e32 v50, v20
	v_mov_b32_e32 v51, v20
	v_mov_b32_e32 v52, v20
	v_mov_b32_e32 v53, v20
	v_mov_b32_e32 v54, v20
	v_mov_b32_e32 v55, v20
	s_waitcnt lgkmcnt(0)
	s_barrier
	v_mul_f32_e32 v230, 0x40b17218, v188
	v_mul_f32_e32 v231, 0x3f800000, v230
	v_mul_f32_e32 v232, 0x40000000, v230
	v_mul_f32_e32 v233, 0x40400000, v230
	v_mul_f32_e32 v234, 0x41800000, v230
	v_mul_f32_e32 v235, 0x41880000, v230
	v_mul_f32_e32 v236, 0x41900000, v230
	v_mul_f32_e32 v237, 0x41980000, v230
	v_mul_f32_e32 v242, 0x42000000, v230
	v_mul_f32_e32 v243, 0x42040000, v230
	v_mul_f32_e32 v244, 0x42080000, v230
	v_mul_f32_e32 v245, 0x420c0000, v230
	v_mul_f32_e32 v246, 0x42400000, v230
	v_mul_f32_e32 v247, 0x42440000, v230
	v_mul_f32_e32 v248, 0x42480000, v230
	v_mul_f32_e32 v249, 0x424c0000, v230
	v_mov_b32_e32 v230, 0

; __device__ __forceinline__ float fexp2(float x) { return __builtin_amdgcn_exp2f(x); }
; template <bool MASKED>
; __device__ __forceinline__ void sm_step(f32x4 (&S)[4], float c1, float slope2, float tb, int kbase, int tqn,
;                                         int window, bool selok, bf16x8 (&pb)[2]) {
; #pragma unroll
;   for (int mt = 0; mt < 4; ++mt)
; #pragma unroll
;     for (int r = 0; r < 4; ++r) {
;       float u = fmaf(slope2, (float)(mt * 16 + r), fmaf(S[mt][r], c1, tb));
;       if (MASKED) {
;         int dist = tqn - (kbase + mt * 16 + r);
;         bool valid = (dist >= 0) && (dist < window) && selok;
;         u = valid ? u : -1e30f;
;       }
;       S[mt][r] = fexp2(u);
;     }
;     ...
; #pragma unroll
;       for (int mp = 0; mp < NMAP; ++mp) {
; #pragma unroll
;         for (int n = 0; n < NQ; ++n) {
;           f32x4 S[4];
; #pragma unroll
;           for (int mt = 0; mt < 4; ++mt) S[mt] = f32x4{0.f, 0.f, 0.f, 0.f};
; #pragma unroll
;           for (int ks = 0; ks < 2; ++ks) {
;             if (NMAP == 2 && ks != mp) continue;
; #pragma unroll
;             for (int mt = 0; mt < 4; ++mt) {
;               bf16x8 a = *(const bf16x8*)(cK + (mt * 16 + l15) * 64 + (((ks * 4 + quad) ^ ((l15 >> 1) & 7)) * 8));
;               S[mt] = mfma16(a, qf[n][ks], S[mt]);
;             }
;           }
;           bf16x8 pb[2];
;           const float tb = slope2 * (float)(kbase - tq[n]);
;           if (full || rowfull) {
;             sm_step<false>(S, c1, slope2, tb, kbase, tq[n], window, true, pb);
;             if (SEL && !full && !selok[n]) {
;               pb[0] = bf16x8{0, 0, 0, 0, 0, 0, 0, 0}; pb[1] = bf16x8{0, 0, 0, 0, 0, 0, 0, 0};
;             }
;           } else sm_step<true>(S, c1, slope2, tb, kbase, tq[n], window, selok[n], pb);
.LBB0_141:
	s_mul_i32 s29, s47, 0x4800
	v_or_b32_e32 v2, s29, v155
	v_add_u32_e32 v3, v2, v157
	ds_read_b128 v[84:87], v3 offset:4096
	ds_read_b128 v[92:95], v3 offset:6144
	v_add_u32_e32 v2, v2, v158
	ds_read_b128 v[76:79], v3
	ds_read_b128 v[108:111], v2 offset:4096
	ds_read_b128 v[80:83], v3 offset:2048
	ds_read_b128 v[96:99], v2
	ds_read_b128 v[104:107], v2 offset:2048
	v_or_b32_e32 v0, s42, v154
	s_waitcnt lgkmcnt(6)
	v_mfma_f32_16x16x32_bf16 v[112:115], v[84:87], v[4:7], v[242:245]
	v_sub_u32_e32 v122, v0, v200
	s_nor_b64 s[42:43], s[18:19], s[30:31]
	s_mov_b64 s[30:31], -1
	s_waitcnt lgkmcnt(3)
	v_mfma_f32_16x16x32_bf16 v[124:127], v[108:111], v[8:11], v[112:115]
	s_and_b64 vcc, exec, s[42:43]
	v_mfma_f32_16x16x32_bf16 v[88:91], v[76:79], v[4:7], v[230:233]
	s_nop 0
	ds_read_b128 v[112:115], v2 offset:6144
	v_cvt_f32_i32_e32 v2, v122
	v_mul_f32_e32 v2, v188, v2
	s_waitcnt lgkmcnt(3)
	v_mfma_f32_16x16x32_bf16 v[100:103], v[80:83], v[4:7], v[234:237]
	v_mfma_f32_16x16x32_bf16 v[116:119], v[92:95], v[4:7], v[246:249]
	s_waitcnt lgkmcnt(2)
	v_mfma_f32_16x16x32_bf16 v[88:91], v[96:99], v[8:11], v[88:91]
	s_waitcnt lgkmcnt(1)
	v_mfma_f32_16x16x32_bf16 v[100:103], v[104:107], v[8:11], v[100:103]
	s_waitcnt lgkmcnt(0)
	v_mfma_f32_16x16x32_bf16 v[118:121], v[112:115], v[8:11], v[116:119]
	s_nop 3
	v_fmamk_f32 v3, v88, 0x3e38aa3b, v2
	v_fmamk_f32 v123, v89, 0x3e38aa3b, v2
	v_fmamk_f32 v88, v90, 0x3e38aa3b, v2
	v_fmamk_f32 v89, v91, 0x3e38aa3b, v2
	v_fmamk_f32 v90, v100, 0x3e38aa3b, v2
	v_fmamk_f32 v91, v101, 0x3e38aa3b, v2
	v_fmamk_f32 v100, v102, 0x3e38aa3b, v2
	v_fmamk_f32 v101, v103, 0x3e38aa3b, v2
	v_fmamk_f32 v102, v124, 0x3e38aa3b, v2
	v_fmamk_f32 v103, v125, 0x3e38aa3b, v2
	v_fmamk_f32 v116, v126, 0x3e38aa3b, v2
	v_fmamk_f32 v117, v127, 0x3e38aa3b, v2
	v_fmamk_f32 v118, v118, 0x3e38aa3b, v2
	v_fmamk_f32 v119, v119, 0x3e38aa3b, v2
	v_fmamk_f32 v120, v120, 0x3e38aa3b, v2
	v_fmac_f32_e32 v2, 0x3e38aa3b, v121
	v_mov_b32_e32 v121, v123
	s_cbranch_vccz .LBB0_143
	v_sub_u32_e32 v123, v200, v0
	v_cmp_gt_u32_e32 vcc, s26, v123
	s_and_b64 vcc, s[40:41], vcc
	v_add_u32_e32 v125, -2, v123
	v_cndmask_b32_e32 v124, v226, v3, vcc
	v_cmp_lt_u32_e32 vcc, s34, v122
	s_and_b64 vcc, s[40:41], vcc
	v_add_u32_e32 v126, -3, v123
	v_cndmask_b32_e32 v122, v226, v121, vcc
	v_cmp_gt_u32_e32 vcc, s26, v125
	s_and_b64 vcc, s[40:41], vcc
	v_add_u32_e32 v127, -16, v123
	v_cndmask_b32_e32 v125, v226, v88, vcc
	v_cmp_gt_u32_e32 vcc, s26, v126
	s_and_b64 vcc, s[40:41], vcc
	v_subrev_u32_e32 v128, 17, v123
	v_cndmask_b32_e32 v126, v226, v89, vcc
	v_cmp_gt_u32_e32 vcc, s26, v127
	s_and_b64 vcc, s[40:41], vcc
	v_subrev_u32_e32 v129, 18, v123
	v_cndmask_b32_e32 v127, v226, v90, vcc
	v_cmp_gt_u32_e32 vcc, s26, v128
	s_and_b64 vcc, s[40:41], vcc
	v_subrev_u32_e32 v130, 19, v123
	v_cndmask_b32_e32 v128, v226, v91, vcc
	v_cmp_gt_u32_e32 vcc, s26, v129
	s_and_b64 vcc, s[40:41], vcc
	v_subrev_u32_e32 v131, 32, v123
	v_cndmask_b32_e32 v129, v226, v100, vcc
	v_cmp_gt_u32_e32 vcc, s26, v130
	s_and_b64 vcc, s[40:41], vcc
	v_subrev_u32_e32 v132, 33, v123
	v_cndmask_b32_e32 v130, v226, v101, vcc
	v_cmp_gt_u32_e32 vcc, s26, v131
	s_and_b64 vcc, s[40:41], vcc
	v_subrev_u32_e32 v133, 34, v123
	v_cndmask_b32_e32 v131, v226, v102, vcc
	v_cmp_gt_u32_e32 vcc, s26, v132
	s_and_b64 vcc, s[40:41], vcc
	v_subrev_u32_e32 v134, 35, v123
	v_cndmask_b32_e32 v132, v226, v103, vcc
	v_cmp_gt_u32_e32 vcc, s26, v133
	s_and_b64 vcc, s[40:41], vcc
	v_subrev_u32_e32 v135, 48, v123
	v_cndmask_b32_e32 v133, v226, v116, vcc
	v_cmp_gt_u32_e32 vcc, s26, v134
	s_and_b64 vcc, s[40:41], vcc
	v_subrev_u32_e32 v136, 49, v123
	v_cndmask_b32_e32 v134, v226, v117, vcc
	v_cmp_gt_u32_e32 vcc, s26, v135
	s_and_b64 vcc, s[40:41], vcc
	v_subrev_u32_e32 v137, 50, v123
	v_cndmask_b32_e32 v135, v226, v118, vcc
	v_cmp_gt_u32_e32 vcc, s26, v136
	s_and_b64 vcc, s[40:41], vcc
	v_subrev_u32_e32 v123, 51, v123
	v_cndmask_b32_e32 v136, v226, v119, vcc
	v_cmp_gt_u32_e32 vcc, s26, v137
	s_and_b64 vcc, s[40:41], vcc
	v_exp_f32_e32 v124, v124
	v_cndmask_b32_e32 v137, v226, v120, vcc
	v_cmp_gt_u32_e32 vcc, s26, v123
	s_and_b64 vcc, s[40:41], vcc
	v_exp_f32_e32 v122, v122
	v_cndmask_b32_e32 v123, v226, v2, vcc
	v_exp_f32_e32 v125, v125
	v_exp_f32_e32 v126, v126
	v_exp_f32_e32 v127, v127
	v_exp_f32_e32 v128, v128
	v_exp_f32_e32 v129, v129
	v_exp_f32_e32 v130, v130
	v_exp_f32_e32 v131, v131
	v_exp_f32_e32 v132, v132
	v_exp_f32_e32 v133, v133
	v_exp_f32_e32 v134, v134
	v_exp_f32_e32 v135, v135
	v_exp_f32_e32 v136, v136
	v_exp_f32_e32 v137, v137
	v_exp_f32_e32 v123, v123
	v_cvt_pk_bf16_f32 v124, v124, v122
	v_cvt_pk_bf16_f32 v125, v125, v126
	v_cvt_pk_bf16_f32 v126, v127, v128
	v_cvt_pk_bf16_f32 v127, v129, v130
	v_cvt_pk_bf16_f32 v140, v131, v132
	v_cvt_pk_bf16_f32 v141, v133, v134
	v_cvt_pk_bf16_f32 v142, v135, v136
	v_cvt_pk_bf16_f32 v143, v137, v123
	s_mov_b64 s[30:31], 0

;     ...
;         for (int n = 0; n < NQ; ++n) {
;           f32x4 S[4];
; #pragma unroll
;           for (int mt = 0; mt < 4; ++mt) S[mt] = f32x4{0.f, 0.f, 0.f, 0.f};
; #pragma unroll
;           for (int ks = 0; ks < 2; ++ks) {
;             if (NMAP == 2 && ks != mp) continue;
; #pragma unroll
;             for (int mt = 0; mt < 4; ++mt) {
;               bf16x8 a = *(const bf16x8*)(cK + (mt * 16 + l15) * 64 + (((ks * 4 + quad) ^ ((l15 >> 1) & 7)) * 8));
;               S[mt] = mfma16(a, qf[n][ks], S[mt]);
;             }
;           }
;           bf16x8 pb[2];
;           const float tb = slope2 * (float)(kbase - tq[n]);
;           if (full || rowfull) {
;             sm_step<false>(S, c1, slope2, tb, kbase, tq[n], window, true, pb);
;             if (SEL && !full && !selok[n]) {
;               pb[0] = bf16x8{0, 0, 0, 0, 0, 0, 0, 0}; pb[1] = bf16x8{0, 0, 0, 0, 0, 0, 0, 0};
;             }
;           } else sm_step<true>(S, c1, slope2, tb, kbase, tq[n], window, selok[n], pb);
; #pragma unroll
;           for (int k2 = 0; k2 < 2; ++k2) {
; #pragma unroll
;             for (int dt = 0; dt < 4; ++dt) {
;               bf16x8 a = vt_frag(cV, dt, k2, l15, quad);
;               O[mp * NQ + n][dt] = mfma16(a, pb[k2], O[mp * NQ + n][dt]);
;             }
;             L[mp * NQ + n] = mfma16(ones, pb[k2], L[mp * NQ + n]);
;           }
.LBB0_147:
	v_lshlrev_b32_e32 v2, 1, v154
	v_add3_u32 v2, s29, v2, v156
	v_add_u32_e32 v3, 0x2000, v2
	v_add_u32_e32 v128, 0x2800, v2
	v_add_u32_e32 v132, 0x3000, v2
	v_add_u32_e32 v2, 0x3800, v2
	ds_read2_b64 v[88:91], v3 offset0:128 offset1:132
	ds_read2_b64 v[100:103], v128 offset0:160 offset1:164
	ds_read2_b64 v[116:119], v132 offset0:192 offset1:196
	ds_read2_b64 v[120:123], v2 offset0:224 offset1:228
	s_mov_b32 s30, s28
	s_mov_b32 s31, s28
	s_mov_b32 s29, s28
	v_mov_b64_e32 v[162:163], s[30:31]
	v_mov_b64_e32 v[160:161], s[28:29]
	s_waitcnt lgkmcnt(3)
	v_mfma_f32_16x16x32_bf16 v[52:55], v[88:91], v[124:127], v[52:55]
	ds_read2_b64 v[128:131], v128 offset0:168 offset1:172
	ds_read2_b64 v[132:135], v132 offset0:200 offset1:204
	ds_read2_b64 v[136:139], v2 offset0:232 offset1:236
	s_waitcnt lgkmcnt(5)
	v_mfma_f32_16x16x32_bf16 v[48:51], v[100:103], v[124:127], v[48:51]
	s_mov_b64 s[30:31], -1
	s_andn2_b64 vcc, exec, s[42:43]
	s_waitcnt lgkmcnt(4)
	v_mfma_f32_16x16x32_bf16 v[44:47], v[116:119], v[124:127], v[44:47]
	s_waitcnt lgkmcnt(3)
	v_mfma_f32_16x16x32_bf16 v[40:43], v[120:123], v[124:127], v[40:43]
	v_mfma_f32_16x16x32_bf16 v[56:59], v[160:163], v[124:127], v[56:59]
	ds_read2_b64 v[124:127], v3 offset0:136 offset1:140
	v_mfma_f32_16x16x32_bf16 v[76:79], v[76:79], v[12:15], v[230:233]
	v_mfma_f32_16x16x32_bf16 v[80:83], v[80:83], v[12:15], v[234:237]
	v_mfma_f32_16x16x32_bf16 v[84:87], v[84:87], v[12:15], v[242:245]
	v_mfma_f32_16x16x32_bf16 v[92:95], v[92:95], v[12:15], v[246:249]
	v_mfma_f32_16x16x32_bf16 v[96:99], v[96:99], v[16:19], v[76:79]
	s_nop 3
	v_sub_u32_e32 v76, v0, v201
	v_cvt_f32_i32_e32 v2, v76
	v_mfma_f32_16x16x32_bf16 v[78:81], v[104:107], v[16:19], v[80:83]
	v_mul_f32_e32 v2, v188, v2
	v_mfma_f32_16x16x32_bf16 v[104:107], v[108:111], v[16:19], v[84:87]
	v_fmamk_f32 v3, v96, 0x3e38aa3b, v2
	v_fmamk_f32 v77, v97, 0x3e38aa3b, v2
	v_mfma_f32_16x16x32_bf16 v[108:111], v[112:115], v[16:19], v[92:95]
	v_fmamk_f32 v84, v98, 0x3e38aa3b, v2
	v_fmamk_f32 v85, v99, 0x3e38aa3b, v2
	v_fmamk_f32 v86, v78, 0x3e38aa3b, v2
	s_waitcnt lgkmcnt(0)
	v_mfma_f32_16x16x32_bf16 v[52:55], v[124:127], v[140:143], v[52:55]
	v_fmamk_f32 v87, v79, 0x3e38aa3b, v2
	v_fmamk_f32 v92, v80, 0x3e38aa3b, v2
	v_fmamk_f32 v93, v81, 0x3e38aa3b, v2
	v_mfma_f32_16x16x32_bf16 v[48:51], v[128:131], v[140:143], v[48:51]
	v_fmamk_f32 v94, v104, 0x3e38aa3b, v2
	v_fmamk_f32 v95, v105, 0x3e38aa3b, v2
	v_fmamk_f32 v96, v106, 0x3e38aa3b, v2
	v_mfma_f32_16x16x32_bf16 v[44:47], v[132:135], v[140:143], v[44:47]
	v_fmamk_f32 v97, v107, 0x3e38aa3b, v2
	v_fmamk_f32 v98, v108, 0x3e38aa3b, v2
	v_fmamk_f32 v99, v109, 0x3e38aa3b, v2
	v_mfma_f32_16x16x32_bf16 v[40:43], v[136:139], v[140:143], v[40:43]
	v_fmamk_f32 v104, v110, 0x3e38aa3b, v2
	v_fmac_f32_e32 v2, 0x3e38aa3b, v111
	v_mov_b32_e32 v105, v77
	v_mfma_f32_16x16x32_bf16 v[56:59], v[160:163], v[140:143], v[56:59]
	s_cbranch_vccnz .LBB0_149
	v_sub_u32_e32 v0, v201, v0
	v_cmp_gt_u32_e32 vcc, s26, v0
	s_and_b64 vcc, s[38:39], vcc
	v_add_u32_e32 v78, -2, v0
	v_cndmask_b32_e32 v77, v226, v3, vcc
	v_cmp_lt_u32_e32 vcc, s34, v76
	s_and_b64 vcc, s[38:39], vcc
	v_add_u32_e32 v79, -3, v0
	v_cndmask_b32_e32 v76, v226, v105, vcc
	v_cmp_gt_u32_e32 vcc, s26, v78
	s_and_b64 vcc, s[38:39], vcc
	v_add_u32_e32 v80, -16, v0
	v_cndmask_b32_e32 v78, v226, v84, vcc
	v_cmp_gt_u32_e32 vcc, s26, v79
	s_and_b64 vcc, s[38:39], vcc
	v_exp_f32_e32 v77, v77
	v_cndmask_b32_e32 v79, v226, v85, vcc
	v_cmp_gt_u32_e32 vcc, s26, v80
	s_and_b64 vcc, s[38:39], vcc
	v_exp_f32_e32 v76, v76
	v_cndmask_b32_e32 v80, v226, v86, vcc
	v_exp_f32_e32 v82, v80
	v_subrev_u32_e32 v80, 17, v0
	v_cmp_gt_u32_e32 vcc, s26, v80
	s_and_b64 vcc, s[38:39], vcc
	v_exp_f32_e32 v78, v78
	v_cndmask_b32_e32 v80, v226, v87, vcc
	v_exp_f32_e32 v83, v80
	v_subrev_u32_e32 v80, 18, v0
	v_cmp_gt_u32_e32 vcc, s26, v80
	s_and_b64 vcc, s[38:39], vcc
	v_exp_f32_e32 v79, v79
	v_cndmask_b32_e32 v80, v226, v92, vcc
	v_exp_f32_e32 v106, v80
	v_subrev_u32_e32 v80, 19, v0
	v_cmp_gt_u32_e32 vcc, s26, v80
	s_and_b64 vcc, s[38:39], vcc
	v_cvt_pk_bf16_f32 v81, v78, v79
	v_cndmask_b32_e32 v80, v226, v93, vcc
	v_exp_f32_e32 v107, v80
	v_subrev_u32_e32 v80, 32, v0
	v_cmp_gt_u32_e32 vcc, s26, v80
	s_and_b64 vcc, s[38:39], vcc
	v_cvt_pk_bf16_f32 v82, v82, v83
	v_cndmask_b32_e32 v80, v226, v94, vcc
	v_exp_f32_e32 v108, v80
	v_subrev_u32_e32 v80, 33, v0
	v_cmp_gt_u32_e32 vcc, s26, v80
	s_and_b64 vcc, s[38:39], vcc
	v_cvt_pk_bf16_f32 v83, v106, v107
	v_cndmask_b32_e32 v80, v226, v95, vcc
	v_exp_f32_e32 v109, v80
	v_subrev_u32_e32 v80, 34, v0
	v_cmp_gt_u32_e32 vcc, s26, v80
	s_and_b64 vcc, s[38:39], vcc
	s_mov_b64 s[30:31], 0
	v_cndmask_b32_e32 v80, v226, v96, vcc
	v_exp_f32_e32 v110, v80
	v_subrev_u32_e32 v80, 35, v0
	v_cmp_gt_u32_e32 vcc, s26, v80
	s_and_b64 vcc, s[38:39], vcc
	s_nop 0
	v_cndmask_b32_e32 v80, v226, v97, vcc
	v_exp_f32_e32 v111, v80
	v_subrev_u32_e32 v80, 48, v0
	v_cmp_gt_u32_e32 vcc, s26, v80
	s_and_b64 vcc, s[38:39], vcc
	s_nop 0
	v_cndmask_b32_e32 v80, v226, v98, vcc
	v_exp_f32_e32 v112, v80
	v_subrev_u32_e32 v80, 49, v0
	v_cmp_gt_u32_e32 vcc, s26, v80
	s_and_b64 vcc, s[38:39], vcc
	s_nop 0
	v_cndmask_b32_e32 v80, v226, v99, vcc
	v_exp_f32_e32 v113, v80
	v_subrev_u32_e32 v80, 50, v0
	v_cmp_gt_u32_e32 vcc, s26, v80
	s_and_b64 vcc, s[38:39], vcc
	v_subrev_u32_e32 v0, 51, v0
	v_cndmask_b32_e32 v80, v226, v104, vcc
	v_cmp_gt_u32_e32 vcc, s26, v0
	s_and_b64 vcc, s[38:39], vcc
	v_exp_f32_e32 v114, v80
	v_cndmask_b32_e32 v0, v226, v2, vcc
	v_exp_f32_e32 v0, v0
	v_cvt_pk_bf16_f32 v80, v77, v76
	v_cvt_pk_bf16_f32 v76, v108, v109
	v_cvt_pk_bf16_f32 v77, v110, v111
	v_cvt_pk_bf16_f32 v78, v112, v113
	v_cvt_pk_bf16_f32 v79, v114, v0
